# grid barrier: spinners watch the top-level arrival counter reaching (generation+1)*XCDs instead of a generation word bumped after a returning atomic
# baseline (speedup 1.0000x reference)
.LBB0_165:
	s_or_b64 exec, exec, s[10:11]
	v_cvt_f32_u32_e32 v4, v2
	s_waitcnt vmcnt(0)
	v_readfirstlane_b32 s3, v3
	v_sub_u32_e32 v3, 0, v2
	v_rcp_iflag_f32_e32 v4, v4
	v_add_u32_e32 v5, s3, v1
	v_mul_f32_e32 v4, 0x4f7ffffe, v4
	v_cvt_u32_f32_e32 v4, v4
	v_mul_lo_u32 v1, v3, v4
	v_mul_hi_u32 v1, v4, v1
	v_add_u32_e32 v1, v4, v1
	v_mul_hi_u32 v1, v5, v1
	v_mul_lo_u32 v3, v1, v2
	v_sub_u32_e32 v3, v5, v3
	v_add_u32_e32 v4, 1, v1
	v_sub_u32_e32 v6, v3, v2
	v_cmp_ge_u32_e32 vcc, v3, v2
	s_nop 1
	v_cndmask_b32_e32 v1, v1, v4, vcc
	v_cndmask_b32_e32 v3, v3, v6, vcc
	v_add_u32_e32 v4, 1, v1
	v_cmp_ge_u32_e32 vcc, v3, v2
	v_add_u32_e32 v3, 1, v5
	s_nop 0
	v_cndmask_b32_e32 v1, v1, v4, vcc
	v_mul_lo_u32 v4, v2, v1
	v_add_u32_e32 v2, v4, v2
	v_cmp_ne_u32_e32 vcc, v3, v2
	s_and_saveexec_b64 s[8:9], vcc
	s_xor_b64 s[8:9], exec, s[8:9]
	s_cbranch_execz .LBB0_179
	s_waitcnt lgkmcnt(0)
	v_mov_b32_e32 v0, 0x20004
	ds_read_b32 v0, v0
	s_waitcnt lgkmcnt(0)
	v_add_u32_e32 v1, 1, v1
	v_mul_lo_u32 v1, v1, v0
	v_mov_b32_e32 v0, 0x3000
	buffer_inv sc1
	global_load_dword v0, v0, s[54:55] offset:1024 sc1
	s_add_u32 s12, s54, 0x3400
	s_addc_u32 s13, s55, 0
	s_waitcnt vmcnt(0)
	v_cmp_gt_u32_e32 vcc, v1, v0
	s_and_saveexec_b64 s[10:11], vcc
	s_cbranch_execz .LBB0_178
	s_mov_b32 s3, 1
	s_mov_b64 s[14:15], 0
	v_mov_b32_e32 v0, 0
	s_branch .LBB0_169

.LBB0_171:
	global_load_dword v2, v0, s[12:13] sc1
	s_add_i32 s3, s3, 1
	s_mov_b64 s[20:21], -1
	s_waitcnt vmcnt(0)
	v_cmp_le_u32_e32 vcc, v1, v2
	s_orn2_b64 s[18:19], vcc, exec
	s_branch .LBB0_168

.LBB0_182:
	s_or_b64 exec, exec, s[10:11]
	v_cvt_f32_u32_e32 v3, v0
	s_waitcnt vmcnt(0)
	v_readfirstlane_b32 s3, v2
	v_sub_u32_e32 v2, 0, v0
	s_add_u32 s8, s54, 0x3500
	v_rcp_iflag_f32_e32 v3, v3
	v_add_u32_e32 v1, s3, v1
	v_add_u32_e32 v4, 1, v1
	s_addc_u32 s9, s55, 0
	v_mul_f32_e32 v3, 0x4f7ffffe, v3
	v_cvt_u32_f32_e32 v3, v3
	s_mov_b64 s[12:13], -1
	v_mul_lo_u32 v2, v2, v3
	v_mul_hi_u32 v2, v3, v2
	v_add_u32_e32 v2, v3, v2
	v_mul_hi_u32 v2, v1, v2
	v_mul_lo_u32 v3, v2, v0
	v_sub_u32_e32 v1, v1, v3
	v_add_u32_e32 v5, 1, v2
	v_sub_u32_e32 v3, v1, v0
	v_cmp_ge_u32_e32 vcc, v1, v0
	s_nop 1
	v_cndmask_b32_e32 v2, v2, v5, vcc
	v_cndmask_b32_e32 v1, v1, v3, vcc
	v_add_u32_e32 v3, 1, v2
	v_cmp_ge_u32_e32 vcc, v1, v0
	s_nop 1
	v_cndmask_b32_e32 v2, v2, v3, vcc
	v_mul_lo_u32 v1, v0, v2
	v_add_u32_e32 v0, v1, v0
	v_cmp_ne_u32_e32 vcc, v4, v0
	v_mov_b32_e32 v2, v0
	v_mov_b64_e32 v[0:1], s[8:9]
	s_and_saveexec_b64 s[10:11], vcc
	s_cbranch_execz .LBB0_194
	v_mov_b32_e32 v0, 0
	global_load_dword v1, v0, s[8:9] offset:-256 sc1
	s_mov_b64 s[16:17], 0
	s_waitcnt vmcnt(0)
	v_cmp_gt_u32_e32 vcc, v2, v1
	s_and_saveexec_b64 s[14:15], vcc
	s_cbranch_execz .LBB0_193
	s_add_u32 s12, s54, 0x200
	s_addc_u32 s13, s55, 0
	s_mov_b32 s3, 1
	s_branch .LBB0_186

.LBB0_188:
	global_load_dword v1, v0, s[8:9] offset:-256 sc1
	s_add_i32 s3, s3, 1
	s_mov_b64 s[20:21], -1
	s_waitcnt vmcnt(0)
	v_cmp_le_u32_e32 vcc, v2, v1
	s_orn2_b64 s[24:25], vcc, exec
	s_branch .LBB0_185

.LBB0_438:
	s_or_b64 exec, exec, s[8:9]
	v_cvt_f32_u32_e32 v4, v2
	s_waitcnt vmcnt(0)
	v_readfirstlane_b32 s3, v3
	v_sub_u32_e32 v3, 0, v2
	v_rcp_iflag_f32_e32 v4, v4
	v_add_u32_e32 v5, s3, v1
	v_mul_f32_e32 v4, 0x4f7ffffe, v4
	v_cvt_u32_f32_e32 v4, v4
	v_mul_lo_u32 v1, v3, v4
	v_mul_hi_u32 v1, v4, v1
	v_add_u32_e32 v1, v4, v1
	v_mul_hi_u32 v1, v5, v1
	v_mul_lo_u32 v3, v1, v2
	v_sub_u32_e32 v3, v5, v3
	v_add_u32_e32 v4, 1, v1
	v_cmp_ge_u32_e32 vcc, v3, v2
	s_nop 1
	v_cndmask_b32_e32 v1, v1, v4, vcc
	v_sub_u32_e32 v4, v3, v2
	v_cndmask_b32_e32 v3, v3, v4, vcc
	v_add_u32_e32 v4, 1, v1
	v_cmp_ge_u32_e32 vcc, v3, v2
	v_add_u32_e32 v3, 1, v5
	s_nop 0
	v_cndmask_b32_e32 v1, v1, v4, vcc
	v_mul_lo_u32 v4, v2, v1
	v_add_u32_e32 v2, v4, v2
	v_cmp_ne_u32_e32 vcc, v3, v2
	s_and_saveexec_b64 s[6:7], vcc
	s_xor_b64 s[6:7], exec, s[6:7]
	s_cbranch_execz .LBB0_452
	s_waitcnt lgkmcnt(0)
	v_mov_b32_e32 v0, 0x20004
	ds_read_b32 v0, v0
	s_waitcnt lgkmcnt(0)
	v_add_u32_e32 v1, 1, v1
	v_mul_lo_u32 v1, v1, v0
	v_mov_b32_e32 v0, 0x3000
	buffer_inv sc1
	global_load_dword v0, v0, s[54:55] offset:1024 sc1
	s_add_u32 s10, s54, 0x3400
	s_addc_u32 s11, s55, 0
	s_waitcnt vmcnt(0)
	v_cmp_gt_u32_e32 vcc, v1, v0
	s_and_saveexec_b64 s[8:9], vcc
	s_cbranch_execz .LBB0_451
	s_mov_b32 s3, 1
	s_mov_b64 s[12:13], 0
	v_mov_b32_e32 v0, 0
	s_branch .LBB0_442

.LBB0_444:
	global_load_dword v2, v0, s[10:11] sc1
	s_add_i32 s3, s3, 1
	s_mov_b64 s[18:19], -1
	s_waitcnt vmcnt(0)
	v_cmp_le_u32_e32 vcc, v1, v2
	s_orn2_b64 s[16:17], vcc, exec
	s_branch .LBB0_441

.LBB0_455:
	s_or_b64 exec, exec, s[8:9]
	s_waitcnt vmcnt(0)
	v_readfirstlane_b32 s3, v2
	v_cvt_f32_u32_e32 v2, v0
	v_sub_u32_e32 v3, 0, v0
	v_add_u32_e32 v1, s3, v1
	s_add_u32 s6, s54, 0x3500
	v_rcp_iflag_f32_e32 v2, v2
	s_addc_u32 s7, s55, 0
	s_mov_b64 s[10:11], -1
	v_mul_f32_e32 v2, 0x4f7ffffe, v2
	v_cvt_u32_f32_e32 v2, v2
	v_mul_lo_u32 v3, v3, v2
	v_mul_hi_u32 v3, v2, v3
	v_add_u32_e32 v2, v2, v3
	v_mul_hi_u32 v2, v1, v2
	v_mul_lo_u32 v3, v2, v0
	v_sub_u32_e32 v3, v1, v3
	v_cmp_ge_u32_e32 vcc, v3, v0
	v_add_u32_e32 v4, 1, v2
	v_add_u32_e32 v1, 1, v1
	v_cndmask_b32_e32 v2, v2, v4, vcc
	v_sub_u32_e32 v4, v3, v0
	v_cndmask_b32_e32 v3, v3, v4, vcc
	v_cmp_ge_u32_e32 vcc, v3, v0
	v_add_u32_e32 v3, 1, v2
	s_nop 0
	v_cndmask_b32_e32 v2, v2, v3, vcc
	v_mul_lo_u32 v3, v0, v2
	v_add_u32_e32 v0, v3, v0
	v_cmp_ne_u32_e32 vcc, v1, v0
	v_mov_b32_e32 v2, v0
	v_mov_b64_e32 v[0:1], s[6:7]
	s_and_saveexec_b64 s[8:9], vcc
	s_cbranch_execz .LBB0_467
	v_mov_b32_e32 v0, 0
	global_load_dword v1, v0, s[6:7] offset:-256 sc1
	s_mov_b64 s[14:15], 0
	s_waitcnt vmcnt(0)
	v_cmp_gt_u32_e32 vcc, v2, v1
	s_and_saveexec_b64 s[12:13], vcc
	s_cbranch_execz .LBB0_466
	s_add_u32 s10, s54, 0x200
	s_addc_u32 s11, s55, 0
	s_mov_b32 s3, 1
	s_branch .LBB0_459

.LBB0_461:
	global_load_dword v1, v0, s[6:7] offset:-256 sc1
	s_add_i32 s3, s3, 1
	s_mov_b64 s[18:19], -1
	s_waitcnt vmcnt(0)
	v_cmp_le_u32_e32 vcc, v2, v1
	s_orn2_b64 s[22:23], vcc, exec
	s_branch .LBB0_458

.LBB0_589:
	s_or_b64 exec, exec, s[8:9]
	v_cvt_f32_u32_e32 v3, v0
	s_waitcnt vmcnt(0)
	v_readfirstlane_b32 s3, v2
	s_add_u32 s8, s54, 0x3500
	s_addc_u32 s9, s55, 0
	v_rcp_iflag_f32_e32 v3, v3
	v_add_u32_e32 v1, s3, v1
	v_add_u32_e32 v4, 1, v1
	s_mov_b64 s[10:11], -1
	v_mul_f32_e32 v2, 0x4f7ffffe, v3
	v_cvt_u32_f32_e32 v2, v2
	v_sub_u32_e32 v3, 0, v0
	v_mul_lo_u32 v3, v3, v2
	v_mul_hi_u32 v3, v2, v3
	v_add_u32_e32 v2, v2, v3
	v_mul_hi_u32 v2, v1, v2
	v_mul_lo_u32 v3, v2, v0
	v_sub_u32_e32 v1, v1, v3
	v_add_u32_e32 v5, 1, v2
	v_cmp_ge_u32_e32 vcc, v1, v0
	v_sub_u32_e32 v3, v1, v0
	s_nop 0
	v_cndmask_b32_e32 v2, v2, v5, vcc
	v_cndmask_b32_e32 v1, v1, v3, vcc
	v_add_u32_e32 v3, 1, v2
	v_cmp_ge_u32_e32 vcc, v1, v0
	s_nop 1
	v_cndmask_b32_e32 v2, v2, v3, vcc
	v_mul_lo_u32 v1, v0, v2
	v_add_u32_e32 v0, v1, v0
	v_cmp_ne_u32_e32 vcc, v4, v0
	v_mov_b32_e32 v2, v0
	v_mov_b64_e32 v[0:1], s[8:9]
	s_and_saveexec_b64 s[6:7], vcc
	s_cbranch_execz .LBB0_601
	v_mov_b32_e32 v0, 0
	global_load_dword v1, v0, s[8:9] offset:-256 sc1
	s_mov_b64 s[14:15], 0
	s_waitcnt vmcnt(0)
	v_cmp_gt_u32_e32 vcc, v2, v1
	s_and_saveexec_b64 s[12:13], vcc
	s_cbranch_execz .LBB0_600
	s_add_u32 s10, s54, 0x200
	s_addc_u32 s11, s55, 0
	s_mov_b32 s3, 1
	s_branch .LBB0_593

.LBB0_595:
	global_load_dword v1, v0, s[8:9] offset:-256 sc1
	s_add_i32 s3, s3, 1
	s_mov_b64 s[18:19], -1
	s_waitcnt vmcnt(0)
	v_cmp_le_u32_e32 vcc, v2, v1
	s_orn2_b64 s[22:23], vcc, exec
	s_branch .LBB0_592

.LBB0_818:
	s_or_b64 exec, exec, s[8:9]
	v_cvt_f32_u32_e32 v144, v142
	s_waitcnt vmcnt(0)
	v_readfirstlane_b32 s3, v143
	v_sub_u32_e32 v143, 0, v142
	v_rcp_iflag_f32_e32 v144, v144
	v_add_u32_e32 v145, s3, v141
	v_mul_f32_e32 v144, 0x4f7ffffe, v144
	v_cvt_u32_f32_e32 v144, v144
	v_mul_lo_u32 v141, v143, v144
	v_mul_hi_u32 v141, v144, v141
	v_add_u32_e32 v141, v144, v141
	v_mul_hi_u32 v141, v145, v141
	v_mul_lo_u32 v143, v141, v142
	v_sub_u32_e32 v143, v145, v143
	v_add_u32_e32 v144, 1, v141
	v_cmp_ge_u32_e32 vcc, v143, v142
	s_nop 1
	v_cndmask_b32_e32 v141, v141, v144, vcc
	v_sub_u32_e32 v144, v143, v142
	v_cndmask_b32_e32 v143, v143, v144, vcc
	v_add_u32_e32 v144, 1, v141
	v_cmp_ge_u32_e32 vcc, v143, v142
	v_add_u32_e32 v143, 1, v145
	s_nop 0
	v_cndmask_b32_e32 v141, v141, v144, vcc
	v_mul_lo_u32 v144, v142, v141
	v_add_u32_e32 v142, v144, v142
	v_cmp_ne_u32_e32 vcc, v143, v142
	s_and_saveexec_b64 s[6:7], vcc
	s_xor_b64 s[6:7], exec, s[6:7]
	s_cbranch_execz .LBB0_832
	s_waitcnt lgkmcnt(0)
	v_mov_b32_e32 v140, 0x20004
	ds_read_b32 v140, v140
	s_waitcnt lgkmcnt(0)
	v_add_u32_e32 v141, 1, v141
	v_mul_lo_u32 v141, v141, v140
	v_mov_b32_e32 v140, 0x3000
	buffer_inv sc1
	global_load_dword v140, v140, s[54:55] offset:1024 sc1
	s_add_u32 s12, s54, 0x3400
	s_addc_u32 s13, s55, 0
	s_waitcnt vmcnt(0)
	v_cmp_gt_u32_e32 vcc, v141, v140
	s_and_saveexec_b64 s[8:9], vcc
	s_cbranch_execz .LBB0_831
	s_mov_b32 s3, 1
	s_mov_b64 s[14:15], 0
	v_mov_b32_e32 v140, 0
	s_branch .LBB0_822

.LBB0_824:
	global_load_dword v142, v140, s[12:13] sc1
	s_add_i32 s3, s3, 1
	s_mov_b64 s[20:21], -1
	s_waitcnt vmcnt(0)
	v_cmp_le_u32_e32 vcc, v141, v142
	s_orn2_b64 s[18:19], vcc, exec
	s_branch .LBB0_821

.LBB0_835:
	s_or_b64 exec, exec, s[8:9]
	v_cvt_f32_u32_e32 v143, v140
	s_waitcnt vmcnt(0)
	v_readfirstlane_b32 s3, v142
	s_add_u32 s8, s54, 0x3500
	s_addc_u32 s9, s55, 0
	v_rcp_iflag_f32_e32 v143, v143
	v_add_u32_e32 v141, s3, v141
	v_add_u32_e32 v144, 1, v141
	s_mov_b64 s[12:13], -1
	v_mul_f32_e32 v142, 0x4f7ffffe, v143
	v_cvt_u32_f32_e32 v142, v142
	v_sub_u32_e32 v143, 0, v140
	v_mul_lo_u32 v143, v143, v142
	v_mul_hi_u32 v143, v142, v143
	v_add_u32_e32 v142, v142, v143
	v_mul_hi_u32 v142, v141, v142
	v_mul_lo_u32 v143, v142, v140
	v_sub_u32_e32 v141, v141, v143
	v_add_u32_e32 v145, 1, v142
	v_cmp_ge_u32_e32 vcc, v141, v140
	v_sub_u32_e32 v143, v141, v140
	s_nop 0
	v_cndmask_b32_e32 v142, v142, v145, vcc
	v_cndmask_b32_e32 v141, v141, v143, vcc
	v_add_u32_e32 v143, 1, v142
	v_cmp_ge_u32_e32 vcc, v141, v140
	s_nop 1
	v_cndmask_b32_e32 v142, v142, v143, vcc
	v_mul_lo_u32 v141, v140, v142
	v_add_u32_e32 v140, v141, v140
	v_cmp_ne_u32_e32 vcc, v144, v140
	v_mov_b32_e32 v142, v140
	v_mov_b64_e32 v[140:141], s[8:9]
	s_and_saveexec_b64 s[6:7], vcc
	s_cbranch_execz .LBB0_847
	v_mov_b32_e32 v140, 0
	global_load_dword v141, v140, s[8:9] offset:-256 sc1
	s_mov_b64 s[16:17], 0
	s_waitcnt vmcnt(0)
	v_cmp_gt_u32_e32 vcc, v142, v141
	s_and_saveexec_b64 s[14:15], vcc
	s_cbranch_execz .LBB0_846
	s_add_u32 s12, s54, 0x200
	s_addc_u32 s13, s55, 0
	s_mov_b32 s3, 1
	s_branch .LBB0_839

.LBB0_841:
	global_load_dword v141, v140, s[8:9] offset:-256 sc1
	s_add_i32 s3, s3, 1
	s_mov_b64 s[20:21], -1
	s_waitcnt vmcnt(0)
	v_cmp_le_u32_e32 vcc, v142, v141
	s_orn2_b64 s[24:25], vcc, exec
	s_branch .LBB0_838

.LBB0_881:
	s_or_b64 exec, exec, s[12:13]
	v_cvt_f32_u32_e32 v4, v2
	s_waitcnt vmcnt(0)
	v_readfirstlane_b32 s3, v3
	v_sub_u32_e32 v3, 0, v2
	v_rcp_iflag_f32_e32 v4, v4
	v_add_u32_e32 v5, s3, v1
	v_mul_f32_e32 v4, 0x4f7ffffe, v4
	v_cvt_u32_f32_e32 v4, v4
	v_mul_lo_u32 v1, v3, v4
	v_mul_hi_u32 v1, v4, v1
	v_add_u32_e32 v1, v4, v1
	v_mul_hi_u32 v1, v5, v1
	v_mul_lo_u32 v3, v1, v2
	v_sub_u32_e32 v3, v5, v3
	v_add_u32_e32 v4, 1, v1
	v_cmp_ge_u32_e32 vcc, v3, v2
	s_nop 1
	v_cndmask_b32_e32 v1, v1, v4, vcc
	v_sub_u32_e32 v4, v3, v2
	v_cndmask_b32_e32 v3, v3, v4, vcc
	v_add_u32_e32 v4, 1, v1
	v_cmp_ge_u32_e32 vcc, v3, v2
	v_add_u32_e32 v3, 1, v5
	s_nop 0
	v_cndmask_b32_e32 v1, v1, v4, vcc
	v_mul_lo_u32 v4, v2, v1
	v_add_u32_e32 v2, v4, v2
	v_cmp_ne_u32_e32 vcc, v3, v2
	s_and_saveexec_b64 s[6:7], vcc
	s_xor_b64 s[6:7], exec, s[6:7]
	s_cbranch_execz .LBB0_895
	s_waitcnt lgkmcnt(0)
	v_mov_b32_e32 v0, 0x20004
	ds_read_b32 v0, v0
	s_waitcnt lgkmcnt(0)
	v_add_u32_e32 v1, 1, v1
	v_mul_lo_u32 v1, v1, v0
	v_mov_b32_e32 v0, 0x3000
	buffer_inv sc1
	global_load_dword v0, v0, s[54:55] offset:1024 sc1
	s_add_u32 s14, s54, 0x3400
	s_addc_u32 s15, s55, 0
	s_waitcnt vmcnt(0)
	v_cmp_gt_u32_e32 vcc, v1, v0
	s_and_saveexec_b64 s[12:13], vcc
	s_cbranch_execz .LBB0_894
	s_mov_b32 s3, 1
	s_mov_b64 s[16:17], 0
	v_mov_b32_e32 v0, 0
	s_branch .LBB0_885

.LBB0_887:
	global_load_dword v2, v0, s[14:15] sc1
	s_add_i32 s3, s3, 1
	s_mov_b64 s[22:23], -1
	s_waitcnt vmcnt(0)
	v_cmp_le_u32_e32 vcc, v1, v2
	s_orn2_b64 s[20:21], vcc, exec
	s_branch .LBB0_884

.LBB0_898:
	s_or_b64 exec, exec, s[12:13]
	v_cvt_f32_u32_e32 v3, v0
	s_waitcnt vmcnt(0)
	v_readfirstlane_b32 s3, v2
	s_add_u32 s12, s54, 0x3500
	s_addc_u32 s13, s55, 0
	v_rcp_iflag_f32_e32 v3, v3
	v_add_u32_e32 v1, s3, v1
	v_add_u32_e32 v4, 1, v1
	s_mov_b64 s[14:15], -1
	v_mul_f32_e32 v2, 0x4f7ffffe, v3
	v_cvt_u32_f32_e32 v2, v2
	v_sub_u32_e32 v3, 0, v0
	v_mul_lo_u32 v3, v3, v2
	v_mul_hi_u32 v3, v2, v3
	v_add_u32_e32 v2, v2, v3
	v_mul_hi_u32 v2, v1, v2
	v_mul_lo_u32 v3, v2, v0
	v_sub_u32_e32 v1, v1, v3
	v_add_u32_e32 v5, 1, v2
	v_cmp_ge_u32_e32 vcc, v1, v0
	v_sub_u32_e32 v3, v1, v0
	s_nop 0
	v_cndmask_b32_e32 v2, v2, v5, vcc
	v_cndmask_b32_e32 v1, v1, v3, vcc
	v_add_u32_e32 v3, 1, v2
	v_cmp_ge_u32_e32 vcc, v1, v0
	s_nop 1
	v_cndmask_b32_e32 v2, v2, v3, vcc
	v_mul_lo_u32 v1, v0, v2
	v_add_u32_e32 v0, v1, v0
	v_cmp_ne_u32_e32 vcc, v4, v0
	v_mov_b32_e32 v2, v0
	v_mov_b64_e32 v[0:1], s[12:13]
	s_and_saveexec_b64 s[6:7], vcc
	s_cbranch_execz .LBB0_910
	v_mov_b32_e32 v0, 0
	global_load_dword v1, v0, s[12:13] offset:-256 sc1
	s_mov_b64 s[18:19], 0
	s_waitcnt vmcnt(0)
	v_cmp_gt_u32_e32 vcc, v2, v1
	s_and_saveexec_b64 s[16:17], vcc
	s_cbranch_execz .LBB0_909
	s_add_u32 s14, s54, 0x200
	s_addc_u32 s15, s55, 0
	s_mov_b32 s3, 1
	s_branch .LBB0_902

.LBB0_904:
	global_load_dword v1, v0, s[12:13] offset:-256 sc1
	s_add_i32 s3, s3, 1
	s_mov_b64 s[22:23], -1
	s_waitcnt vmcnt(0)
	v_cmp_le_u32_e32 vcc, v2, v1
	s_orn2_b64 s[26:27], vcc, exec
	s_branch .LBB0_901

.LBB0_948:
	s_or_b64 exec, exec, s[14:15]
	v_cvt_f32_u32_e32 v4, v2
	s_waitcnt vmcnt(0)
	v_readfirstlane_b32 s3, v3
	v_sub_u32_e32 v3, 0, v2
	v_rcp_iflag_f32_e32 v4, v4
	v_add_u32_e32 v5, s3, v1
	v_mul_f32_e32 v4, 0x4f7ffffe, v4
	v_cvt_u32_f32_e32 v4, v4
	v_mul_lo_u32 v1, v3, v4
	v_mul_hi_u32 v1, v4, v1
	v_add_u32_e32 v1, v4, v1
	v_mul_hi_u32 v1, v5, v1
	v_mul_lo_u32 v3, v1, v2
	v_sub_u32_e32 v3, v5, v3
	v_add_u32_e32 v4, 1, v1
	v_cmp_ge_u32_e32 vcc, v3, v2
	s_nop 1
	v_cndmask_b32_e32 v1, v1, v4, vcc
	v_sub_u32_e32 v4, v3, v2
	v_cndmask_b32_e32 v3, v3, v4, vcc
	v_add_u32_e32 v4, 1, v1
	v_cmp_ge_u32_e32 vcc, v3, v2
	v_add_u32_e32 v3, 1, v5
	s_nop 0
	v_cndmask_b32_e32 v1, v1, v4, vcc
	v_mul_lo_u32 v4, v2, v1
	v_add_u32_e32 v2, v4, v2
	v_cmp_ne_u32_e32 vcc, v3, v2
	s_and_saveexec_b64 s[12:13], vcc
	s_xor_b64 s[12:13], exec, s[12:13]
	s_cbranch_execz .LBB0_962
	s_waitcnt lgkmcnt(0)
	v_mov_b32_e32 v0, 0x20004
	ds_read_b32 v0, v0
	s_waitcnt lgkmcnt(0)
	v_add_u32_e32 v1, 1, v1
	v_mul_lo_u32 v1, v1, v0
	v_mov_b32_e32 v0, 0x3000
	buffer_inv sc1
	global_load_dword v0, v0, s[54:55] offset:1024 sc1
	s_add_u32 s16, s54, 0x3400
	s_addc_u32 s17, s55, 0
	s_waitcnt vmcnt(0)
	v_cmp_gt_u32_e32 vcc, v1, v0
	s_and_saveexec_b64 s[14:15], vcc
	s_cbranch_execz .LBB0_961
	s_mov_b32 s3, 1
	s_mov_b64 s[18:19], 0
	v_mov_b32_e32 v0, 0
	s_branch .LBB0_952

.LBB0_954:
	global_load_dword v2, v0, s[16:17] sc1
	s_add_i32 s3, s3, 1
	s_mov_b64 s[24:25], -1
	s_waitcnt vmcnt(0)
	v_cmp_le_u32_e32 vcc, v1, v2
	s_orn2_b64 s[22:23], vcc, exec
	s_branch .LBB0_951

.LBB0_965:
	s_or_b64 exec, exec, s[14:15]
	v_cvt_f32_u32_e32 v3, v0
	s_waitcnt vmcnt(0)
	v_readfirstlane_b32 s3, v2
	s_add_u32 s14, s54, 0x3500
	s_addc_u32 s15, s55, 0
	v_rcp_iflag_f32_e32 v3, v3
	v_add_u32_e32 v1, s3, v1
	v_add_u32_e32 v4, 1, v1
	s_mov_b64 s[16:17], -1
	v_mul_f32_e32 v2, 0x4f7ffffe, v3
	v_cvt_u32_f32_e32 v2, v2
	v_sub_u32_e32 v3, 0, v0
	v_mul_lo_u32 v3, v3, v2
	v_mul_hi_u32 v3, v2, v3
	v_add_u32_e32 v2, v2, v3
	v_mul_hi_u32 v2, v1, v2
	v_mul_lo_u32 v3, v2, v0
	v_sub_u32_e32 v1, v1, v3
	v_add_u32_e32 v5, 1, v2
	v_cmp_ge_u32_e32 vcc, v1, v0
	v_sub_u32_e32 v3, v1, v0
	s_nop 0
	v_cndmask_b32_e32 v2, v2, v5, vcc
	v_cndmask_b32_e32 v1, v1, v3, vcc
	v_add_u32_e32 v3, 1, v2
	v_cmp_ge_u32_e32 vcc, v1, v0
	s_nop 1
	v_cndmask_b32_e32 v2, v2, v3, vcc
	v_mul_lo_u32 v1, v0, v2
	v_add_u32_e32 v0, v1, v0
	v_cmp_ne_u32_e32 vcc, v4, v0
	v_mov_b32_e32 v2, v0
	v_mov_b64_e32 v[0:1], s[14:15]
	s_and_saveexec_b64 s[12:13], vcc
	s_cbranch_execz .LBB0_977
	v_mov_b32_e32 v0, 0
	global_load_dword v1, v0, s[14:15] offset:-256 sc1
	s_mov_b64 s[20:21], 0
	s_waitcnt vmcnt(0)
	v_cmp_gt_u32_e32 vcc, v2, v1
	s_and_saveexec_b64 s[18:19], vcc
	s_cbranch_execz .LBB0_976
	s_add_u32 s16, s54, 0x200
	s_addc_u32 s17, s55, 0
	s_mov_b32 s3, 1
	s_branch .LBB0_969

.LBB0_971:
	global_load_dword v1, v0, s[14:15] offset:-256 sc1
	s_add_i32 s3, s3, 1
	s_mov_b64 s[24:25], -1
	s_waitcnt vmcnt(0)
	v_cmp_le_u32_e32 vcc, v2, v1
	s_orn2_b64 s[28:29], vcc, exec
	s_branch .LBB0_968

.LBB0_1125:
	s_or_b64 exec, exec, s[12:13]
	v_cvt_f32_u32_e32 v4, v2
	s_waitcnt vmcnt(0)
	v_readfirstlane_b32 s3, v3
	v_sub_u32_e32 v3, 0, v2
	v_rcp_iflag_f32_e32 v4, v4
	v_add_u32_e32 v5, s3, v1
	v_mul_f32_e32 v4, 0x4f7ffffe, v4
	v_cvt_u32_f32_e32 v4, v4
	v_mul_lo_u32 v1, v3, v4
	v_mul_hi_u32 v1, v4, v1
	v_add_u32_e32 v1, v4, v1
	v_mul_hi_u32 v1, v5, v1
	v_mul_lo_u32 v3, v1, v2
	v_sub_u32_e32 v3, v5, v3
	v_add_u32_e32 v4, 1, v1
	v_cmp_ge_u32_e32 vcc, v3, v2
	s_nop 1
	v_cndmask_b32_e32 v1, v1, v4, vcc
	v_sub_u32_e32 v4, v3, v2
	v_cndmask_b32_e32 v3, v3, v4, vcc
	v_add_u32_e32 v4, 1, v1
	v_cmp_ge_u32_e32 vcc, v3, v2
	v_add_u32_e32 v3, 1, v5
	s_nop 0
	v_cndmask_b32_e32 v1, v1, v4, vcc
	v_mul_lo_u32 v4, v2, v1
	v_add_u32_e32 v2, v4, v2
	v_cmp_ne_u32_e32 vcc, v3, v2
	s_and_saveexec_b64 s[10:11], vcc
	s_xor_b64 s[10:11], exec, s[10:11]
	s_cbranch_execz .LBB0_1139
	s_waitcnt lgkmcnt(0)
	v_mov_b32_e32 v0, 0x20004
	ds_read_b32 v0, v0
	s_waitcnt lgkmcnt(0)
	v_add_u32_e32 v1, 1, v1
	v_mul_lo_u32 v1, v1, v0
	v_mov_b32_e32 v0, 0x3000
	buffer_inv sc1
	global_load_dword v0, v0, s[54:55] offset:1024 sc1
	s_add_u32 s14, s54, 0x3400
	s_addc_u32 s15, s55, 0
	s_waitcnt vmcnt(0)
	v_cmp_gt_u32_e32 vcc, v1, v0
	s_and_saveexec_b64 s[12:13], vcc
	s_cbranch_execz .LBB0_1138
	s_mov_b32 s3, 1
	s_mov_b64 s[16:17], 0
	v_mov_b32_e32 v0, 0
	s_branch .LBB0_1129

.LBB0_1142:
	s_or_b64 exec, exec, s[12:13]
	v_cvt_f32_u32_e32 v3, v0
	s_waitcnt vmcnt(0)
	v_readfirstlane_b32 s3, v2
	s_add_u32 s12, s54, 0x3500
	s_addc_u32 s13, s55, 0
	v_rcp_iflag_f32_e32 v3, v3
	v_add_u32_e32 v1, s3, v1
	v_add_u32_e32 v4, 1, v1
	s_mov_b64 s[14:15], -1
	v_mul_f32_e32 v2, 0x4f7ffffe, v3
	v_cvt_u32_f32_e32 v2, v2
	v_sub_u32_e32 v3, 0, v0
	v_mul_lo_u32 v3, v3, v2
	v_mul_hi_u32 v3, v2, v3
	v_add_u32_e32 v2, v2, v3
	v_mul_hi_u32 v2, v1, v2
	v_mul_lo_u32 v3, v2, v0
	v_sub_u32_e32 v1, v1, v3
	v_add_u32_e32 v5, 1, v2
	v_cmp_ge_u32_e32 vcc, v1, v0
	v_sub_u32_e32 v3, v1, v0
	s_nop 0
	v_cndmask_b32_e32 v2, v2, v5, vcc
	v_cndmask_b32_e32 v1, v1, v3, vcc
	v_add_u32_e32 v3, 1, v2
	v_cmp_ge_u32_e32 vcc, v1, v0
	s_nop 1
	v_cndmask_b32_e32 v2, v2, v3, vcc
	v_mul_lo_u32 v1, v0, v2
	v_add_u32_e32 v0, v1, v0
	v_cmp_ne_u32_e32 vcc, v4, v0
	v_mov_b32_e32 v2, v0
	v_mov_b64_e32 v[0:1], s[12:13]
	s_and_saveexec_b64 s[10:11], vcc
	s_cbranch_execz .LBB0_1154
	v_mov_b32_e32 v0, 0
	global_load_dword v1, v0, s[12:13] offset:-256 sc1
	s_mov_b64 s[18:19], 0
	s_waitcnt vmcnt(0)
	v_cmp_gt_u32_e32 vcc, v2, v1
	s_and_saveexec_b64 s[16:17], vcc
	s_cbranch_execz .LBB0_1153
	s_add_u32 s14, s54, 0x200
	s_addc_u32 s15, s55, 0
	s_mov_b32 s3, 1
	s_branch .LBB0_1146

.LBB0_1209:
	s_or_b64 exec, exec, s[12:13]
	v_cvt_f32_u32_e32 v144, v142
	s_waitcnt vmcnt(0)
	v_readfirstlane_b32 s3, v143
	v_sub_u32_e32 v143, 0, v142
	v_rcp_iflag_f32_e32 v144, v144
	v_add_u32_e32 v145, s3, v141
	v_mul_f32_e32 v144, 0x4f7ffffe, v144
	v_cvt_u32_f32_e32 v144, v144
	v_mul_lo_u32 v141, v143, v144
	v_mul_hi_u32 v141, v144, v141
	v_add_u32_e32 v141, v144, v141
	v_mul_hi_u32 v141, v145, v141
	v_mul_lo_u32 v143, v141, v142
	v_sub_u32_e32 v143, v145, v143
	v_add_u32_e32 v144, 1, v141
	v_cmp_ge_u32_e32 vcc, v143, v142
	s_nop 1
	v_cndmask_b32_e32 v141, v141, v144, vcc
	v_sub_u32_e32 v144, v143, v142
	v_cndmask_b32_e32 v143, v143, v144, vcc
	v_add_u32_e32 v144, 1, v141
	v_cmp_ge_u32_e32 vcc, v143, v142
	v_add_u32_e32 v143, 1, v145
	s_nop 0
	v_cndmask_b32_e32 v141, v141, v144, vcc
	v_mul_lo_u32 v144, v142, v141
	v_add_u32_e32 v142, v144, v142
	v_cmp_ne_u32_e32 vcc, v143, v142
	s_and_saveexec_b64 s[10:11], vcc
	s_xor_b64 s[10:11], exec, s[10:11]
	s_cbranch_execz .LBB0_1223
	s_waitcnt lgkmcnt(0)
	v_mov_b32_e32 v140, 0x20004
	ds_read_b32 v140, v140
	s_waitcnt lgkmcnt(0)
	v_add_u32_e32 v141, 1, v141
	v_mul_lo_u32 v141, v141, v140
	v_mov_b32_e32 v140, 0x3000
	buffer_inv sc1
	global_load_dword v140, v140, s[54:55] offset:1024 sc1
	s_add_u32 s14, s54, 0x3400
	s_addc_u32 s15, s55, 0
	s_waitcnt vmcnt(0)
	v_cmp_gt_u32_e32 vcc, v141, v140
	s_and_saveexec_b64 s[12:13], vcc
	s_cbranch_execz .LBB0_1222
	s_mov_b32 s3, 1
	s_mov_b64 s[16:17], 0
	v_mov_b32_e32 v140, 0
	s_branch .LBB0_1213

.LBB0_1215:
	global_load_dword v142, v140, s[14:15] sc1
	s_add_i32 s3, s3, 1
	s_mov_b64 s[22:23], -1
	s_waitcnt vmcnt(0)
	v_cmp_le_u32_e32 vcc, v141, v142
	s_orn2_b64 s[20:21], vcc, exec
	s_branch .LBB0_1212

.LBB0_1226:
	s_or_b64 exec, exec, s[12:13]
	v_cvt_f32_u32_e32 v143, v140
	s_waitcnt vmcnt(0)
	v_readfirstlane_b32 s3, v142
	s_add_u32 s12, s54, 0x3500
	s_addc_u32 s13, s55, 0
	v_rcp_iflag_f32_e32 v143, v143
	v_add_u32_e32 v141, s3, v141
	v_add_u32_e32 v144, 1, v141
	s_mov_b64 s[14:15], -1
	v_mul_f32_e32 v142, 0x4f7ffffe, v143
	v_cvt_u32_f32_e32 v142, v142
	v_sub_u32_e32 v143, 0, v140
	v_mul_lo_u32 v143, v143, v142
	v_mul_hi_u32 v143, v142, v143
	v_add_u32_e32 v142, v142, v143
	v_mul_hi_u32 v142, v141, v142
	v_mul_lo_u32 v143, v142, v140
	v_sub_u32_e32 v141, v141, v143
	v_add_u32_e32 v145, 1, v142
	v_cmp_ge_u32_e32 vcc, v141, v140
	v_sub_u32_e32 v143, v141, v140
	s_nop 0
	v_cndmask_b32_e32 v142, v142, v145, vcc
	v_cndmask_b32_e32 v141, v141, v143, vcc
	v_add_u32_e32 v143, 1, v142
	v_cmp_ge_u32_e32 vcc, v141, v140
	s_nop 1
	v_cndmask_b32_e32 v142, v142, v143, vcc
	v_mul_lo_u32 v141, v140, v142
	v_add_u32_e32 v140, v141, v140
	v_cmp_ne_u32_e32 vcc, v144, v140
	v_mov_b32_e32 v142, v140
	v_mov_b64_e32 v[140:141], s[12:13]
	s_and_saveexec_b64 s[10:11], vcc
	s_cbranch_execz .LBB0_1238
	v_mov_b32_e32 v140, 0
	global_load_dword v141, v140, s[12:13] offset:-256 sc1
	s_mov_b64 s[18:19], 0
	s_waitcnt vmcnt(0)
	v_cmp_gt_u32_e32 vcc, v142, v141
	s_and_saveexec_b64 s[16:17], vcc
	s_cbranch_execz .LBB0_1237
	s_add_u32 s14, s54, 0x200
	s_addc_u32 s15, s55, 0
	s_mov_b32 s3, 1
	s_branch .LBB0_1230

.LBB0_1232:
	global_load_dword v141, v140, s[12:13] offset:-256 sc1
	s_add_i32 s3, s3, 1
	s_mov_b64 s[22:23], -1
	s_waitcnt vmcnt(0)
	v_cmp_le_u32_e32 vcc, v142, v141
	s_orn2_b64 s[26:27], vcc, exec
	s_branch .LBB0_1229

.LBB0_1434:
	s_or_b64 exec, exec, s[10:11]
	v_cvt_f32_u32_e32 v144, v142
	s_waitcnt vmcnt(0)
	v_readfirstlane_b32 s3, v143
	v_sub_u32_e32 v143, 0, v142
	v_rcp_iflag_f32_e32 v144, v144
	v_add_u32_e32 v145, s3, v141
	v_mul_f32_e32 v144, 0x4f7ffffe, v144
	v_cvt_u32_f32_e32 v144, v144
	v_mul_lo_u32 v141, v143, v144
	v_mul_hi_u32 v141, v144, v141
	v_add_u32_e32 v141, v144, v141
	v_mul_hi_u32 v141, v145, v141
	v_mul_lo_u32 v143, v141, v142
	v_sub_u32_e32 v143, v145, v143
	v_add_u32_e32 v144, 1, v141
	v_cmp_ge_u32_e32 vcc, v143, v142
	s_nop 1
	v_cndmask_b32_e32 v141, v141, v144, vcc
	v_sub_u32_e32 v144, v143, v142
	v_cndmask_b32_e32 v143, v143, v144, vcc
	v_add_u32_e32 v144, 1, v141
	v_cmp_ge_u32_e32 vcc, v143, v142
	v_add_u32_e32 v143, 1, v145
	s_nop 0
	v_cndmask_b32_e32 v141, v141, v144, vcc
	v_mul_lo_u32 v144, v142, v141
	v_add_u32_e32 v142, v144, v142
	v_cmp_ne_u32_e32 vcc, v143, v142
	s_and_saveexec_b64 s[8:9], vcc
	s_xor_b64 s[8:9], exec, s[8:9]
	s_cbranch_execz .LBB0_1448
	s_waitcnt lgkmcnt(0)
	v_mov_b32_e32 v140, 0x20004
	ds_read_b32 v140, v140
	s_waitcnt lgkmcnt(0)
	v_add_u32_e32 v141, 1, v141
	v_mul_lo_u32 v141, v141, v140
	v_mov_b32_e32 v140, 0x3000
	buffer_inv sc1
	global_load_dword v140, v140, s[54:55] offset:1024 sc1
	s_add_u32 s12, s54, 0x3400
	s_addc_u32 s13, s55, 0
	s_waitcnt vmcnt(0)
	v_cmp_gt_u32_e32 vcc, v141, v140
	s_and_saveexec_b64 s[10:11], vcc
	s_cbranch_execz .LBB0_1447
	s_mov_b32 s3, 1
	s_mov_b64 s[14:15], 0
	v_mov_b32_e32 v140, 0
	s_branch .LBB0_1438

.LBB0_1451:
	s_or_b64 exec, exec, s[10:11]
	v_cvt_f32_u32_e32 v143, v140
	s_waitcnt vmcnt(0)
	v_readfirstlane_b32 s3, v142
	s_add_u32 s10, s54, 0x3500
	s_addc_u32 s11, s55, 0
	v_rcp_iflag_f32_e32 v143, v143
	v_add_u32_e32 v141, s3, v141
	v_add_u32_e32 v144, 1, v141
	s_mov_b64 s[12:13], -1
	v_mul_f32_e32 v142, 0x4f7ffffe, v143
	v_cvt_u32_f32_e32 v142, v142
	v_sub_u32_e32 v143, 0, v140
	v_mul_lo_u32 v143, v143, v142
	v_mul_hi_u32 v143, v142, v143
	v_add_u32_e32 v142, v142, v143
	v_mul_hi_u32 v142, v141, v142
	v_mul_lo_u32 v143, v142, v140
	v_sub_u32_e32 v141, v141, v143
	v_add_u32_e32 v145, 1, v142
	v_cmp_ge_u32_e32 vcc, v141, v140
	v_sub_u32_e32 v143, v141, v140
	s_nop 0
	v_cndmask_b32_e32 v142, v142, v145, vcc
	v_cndmask_b32_e32 v141, v141, v143, vcc
	v_add_u32_e32 v143, 1, v142
	v_cmp_ge_u32_e32 vcc, v141, v140
	s_nop 1
	v_cndmask_b32_e32 v142, v142, v143, vcc
	v_mul_lo_u32 v141, v140, v142
	v_add_u32_e32 v140, v141, v140
	v_cmp_ne_u32_e32 vcc, v144, v140
	v_mov_b32_e32 v142, v140
	v_mov_b64_e32 v[140:141], s[10:11]
	s_and_saveexec_b64 s[8:9], vcc
	s_cbranch_execz .LBB0_1463
	v_mov_b32_e32 v140, 0
	global_load_dword v141, v140, s[10:11] offset:-256 sc1
	s_mov_b64 s[16:17], 0
	s_waitcnt vmcnt(0)
	v_cmp_gt_u32_e32 vcc, v142, v141
	s_and_saveexec_b64 s[14:15], vcc
	s_cbranch_execz .LBB0_1462
	s_add_u32 s12, s54, 0x200
	s_addc_u32 s13, s55, 0
	s_mov_b32 s3, 1
	s_branch .LBB0_1455

.LBB0_1457:
	global_load_dword v141, v140, s[10:11] offset:-256 sc1
	s_add_i32 s3, s3, 1
	s_mov_b64 s[20:21], -1
	s_waitcnt vmcnt(0)
	v_cmp_le_u32_e32 vcc, v142, v141
	s_orn2_b64 s[24:25], vcc, exec
	s_branch .LBB0_1454
